# GEMM main loops: 7 of 16 LDS-DMA loads per iteration take the SGPR-base form (no VALU 64-bit add)
# speedup vs baseline: 1.0543x; 1.0026x over previous
.LBB0_260:
	s_add_u32 s6, s4, 0xfffc0080
	s_addc_u32 s7, s5, -1
	s_add_i32 s35, 0, 0x10000
	s_cmp_eq_u32 s34, 12
	s_cselect_b32 s11, s21, s7
	s_cselect_b32 s10, s26, s6
	v_add_u32_e32 v146, s35, v139
	s_cselect_b32 s7, s19, s29
	s_cselect_b32 s6, s27, s28
	s_add_i32 s92, 0, 0x14000
	ds_read_b128 v[148:151], v146
	ds_read_b128 v[152:155], v146 offset:1024
	ds_read_b128 v[156:159], v146 offset:2048
	ds_read_b128 v[160:163], v146 offset:3072
	v_add_u32_e32 v146, s92, v139
	ds_read_b128 v[170:173], v146
	ds_read_b128 v[174:177], v146 offset:1024
	ds_read_b128 v[178:181], v146 offset:2048
	ds_read_b128 v[182:185], v146 offset:3072
	s_add_i32 m0, s40, 0xc000
	ds_read_b128 v[186:189], v168
	ds_read_b128 v[190:193], v168 offset:1024
	ds_read_b128 v[194:197], v168 offset:2048
	ds_read_b128 v[198:201], v168 offset:3072
	ds_read_b128 v[202:205], v168 offset:4096
	ds_read_b128 v[222:225], v168 offset:5120
	ds_read_b128 v[236:239], v168 offset:6144
	ds_read_b128 v[240:243], v168 offset:7168
	global_load_lds_dwordx4 v142, s[4:5]
	s_add_i32 m0, s40, 0xe000
	s_nop 0
	global_load_lds_dwordx4 v144, s[4:5]
	s_waitcnt vmcnt(8)
	s_waitcnt lgkmcnt(0)
	s_barrier
	s_setprio 1
	s_waitcnt lgkmcnt(0)
	v_mfma_f32_16x16x32_bf16 v[124:127], v[148:151], v[186:189], v[124:127]
	v_mfma_f32_16x16x32_bf16 v[120:123], v[156:159], v[186:189], v[120:123]
	v_mfma_f32_16x16x32_bf16 v[108:111], v[148:151], v[194:197], v[108:111]
	v_mfma_f32_16x16x32_bf16 v[104:107], v[156:159], v[194:197], v[104:107]
	v_mfma_f32_16x16x32_bf16 v[92:95], v[148:151], v[202:205], v[92:95]
	v_mfma_f32_16x16x32_bf16 v[88:91], v[156:159], v[202:205], v[88:91]
	v_mfma_f32_16x16x32_bf16 v[76:79], v[148:151], v[236:239], v[76:79]
	v_mfma_f32_16x16x32_bf16 v[72:75], v[156:159], v[236:239], v[72:75]
	v_mfma_f32_16x16x32_bf16 v[124:127], v[152:155], v[190:193], v[124:127]
	v_mfma_f32_16x16x32_bf16 v[120:123], v[160:163], v[190:193], v[120:123]
	v_mfma_f32_16x16x32_bf16 v[108:111], v[152:155], v[198:201], v[108:111]
	v_mfma_f32_16x16x32_bf16 v[104:107], v[160:163], v[198:201], v[104:107]
	v_mfma_f32_16x16x32_bf16 v[92:95], v[152:155], v[222:225], v[92:95]
	v_mfma_f32_16x16x32_bf16 v[88:91], v[160:163], v[222:225], v[88:91]
	v_mfma_f32_16x16x32_bf16 v[76:79], v[152:155], v[240:243], v[76:79]
	v_mfma_f32_16x16x32_bf16 v[72:75], v[160:163], v[240:243], v[72:75]
	s_setprio 0
	s_setprio 1
	v_mfma_f32_16x16x32_bf16 v[116:119], v[170:173], v[186:189], v[116:119]
	v_mfma_f32_16x16x32_bf16 v[112:115], v[178:181], v[186:189], v[112:115]
	v_mfma_f32_16x16x32_bf16 v[100:103], v[170:173], v[194:197], v[100:103]
	v_mfma_f32_16x16x32_bf16 v[96:99], v[178:181], v[194:197], v[96:99]
	v_mfma_f32_16x16x32_bf16 v[84:87], v[170:173], v[202:205], v[84:87]
	v_mfma_f32_16x16x32_bf16 v[80:83], v[178:181], v[202:205], v[80:83]
	v_mfma_f32_16x16x32_bf16 v[68:71], v[170:173], v[236:239], v[68:71]
	v_mfma_f32_16x16x32_bf16 v[64:67], v[178:181], v[236:239], v[64:67]
	v_mfma_f32_16x16x32_bf16 v[116:119], v[174:177], v[190:193], v[116:119]
	v_mfma_f32_16x16x32_bf16 v[112:115], v[182:185], v[190:193], v[112:115]
	v_mfma_f32_16x16x32_bf16 v[100:103], v[174:177], v[198:201], v[100:103]
	v_mfma_f32_16x16x32_bf16 v[96:99], v[182:185], v[198:201], v[96:99]
	v_mfma_f32_16x16x32_bf16 v[84:87], v[174:177], v[222:225], v[84:87]
	v_mfma_f32_16x16x32_bf16 v[80:83], v[182:185], v[222:225], v[80:83]
	v_mfma_f32_16x16x32_bf16 v[68:71], v[174:177], v[240:243], v[68:71]
	v_mfma_f32_16x16x32_bf16 v[64:67], v[182:185], v[240:243], v[64:67]
	s_setprio 0
	s_barrier
	s_add_i32 s35, s35, s37
	v_lshl_add_u64 v[206:207], s[6:7], 0, v[132:133]
	s_mov_b32 m0, s35
	ds_read_b128 v[186:189], v168 offset:16384
	ds_read_b128 v[190:193], v168 offset:17408
	ds_read_b128 v[194:197], v168 offset:18432
	ds_read_b128 v[198:201], v168 offset:19456
	ds_read_b128 v[202:205], v168 offset:20480
	ds_read_b128 v[222:225], v168 offset:21504
	ds_read_b128 v[236:239], v168 offset:22528
	ds_read_b128 v[240:243], v168 offset:23552
	global_load_lds_dwordx4 v[206:207], off
	s_add_i32 m0, s35, 0x2000
	s_add_u32 vcc_lo, s6, 0x40000
	v_lshl_add_u64 v[244:245], s[6:7], 0, v[128:129]
	s_addc_u32 vcc_hi, s7, 0
	s_add_i32 s35, s92, s37
	global_load_lds_dwordx4 v[244:245], off
	s_mov_b32 m0, s35
	v_lshl_add_u64 v[248:249], s[10:11], 0, v[130:131]
	global_load_lds_dwordx4 v132, vcc
	s_add_i32 m0, s35, 0x2000
	s_nop 0
	global_load_lds_dwordx4 v128, vcc
	v_lshl_add_u64 v[246:247], s[10:11], 0, v[134:135]
	s_mov_b32 m0, s40
	s_nop 0
	global_load_lds_dwordx4 v[246:247], off
	s_mov_b32 m0, s41
	s_nop 0
	global_load_lds_dwordx4 v[248:249], off
	s_waitcnt vmcnt(8)
	s_waitcnt lgkmcnt(0)
	s_barrier
	s_setprio 1
	s_waitcnt lgkmcnt(0)
	v_mfma_f32_16x16x32_bf16 v[60:63], v[148:151], v[186:189], v[60:63]
	v_mfma_f32_16x16x32_bf16 v[56:59], v[156:159], v[186:189], v[56:59]
	v_mfma_f32_16x16x32_bf16 v[44:47], v[148:151], v[194:197], v[44:47]
	v_mfma_f32_16x16x32_bf16 v[40:43], v[156:159], v[194:197], v[40:43]
	v_mfma_f32_16x16x32_bf16 v[28:31], v[148:151], v[202:205], v[28:31]
	v_mfma_f32_16x16x32_bf16 v[24:27], v[156:159], v[202:205], v[24:27]
	v_mfma_f32_16x16x32_bf16 v[12:15], v[148:151], v[236:239], v[12:15]
	v_mfma_f32_16x16x32_bf16 v[8:11], v[156:159], v[236:239], v[8:11]
	v_mfma_f32_16x16x32_bf16 v[60:63], v[152:155], v[190:193], v[60:63]
	v_mfma_f32_16x16x32_bf16 v[56:59], v[160:163], v[190:193], v[56:59]
	v_mfma_f32_16x16x32_bf16 v[44:47], v[152:155], v[198:201], v[44:47]
	v_mfma_f32_16x16x32_bf16 v[40:43], v[160:163], v[198:201], v[40:43]
	v_mfma_f32_16x16x32_bf16 v[28:31], v[152:155], v[222:225], v[28:31]
	v_mfma_f32_16x16x32_bf16 v[24:27], v[160:163], v[222:225], v[24:27]
	v_mfma_f32_16x16x32_bf16 v[12:15], v[152:155], v[240:243], v[12:15]
	v_mfma_f32_16x16x32_bf16 v[8:11], v[160:163], v[240:243], v[8:11]
	s_setprio 0
	s_setprio 1
	v_mfma_f32_16x16x32_bf16 v[52:55], v[170:173], v[186:189], v[52:55]
	v_mfma_f32_16x16x32_bf16 v[48:51], v[178:181], v[186:189], v[48:51]
	v_mfma_f32_16x16x32_bf16 v[36:39], v[170:173], v[194:197], v[36:39]
	v_mfma_f32_16x16x32_bf16 v[32:35], v[178:181], v[194:197], v[32:35]
	v_mfma_f32_16x16x32_bf16 v[20:23], v[170:173], v[202:205], v[20:23]
	v_mfma_f32_16x16x32_bf16 v[16:19], v[178:181], v[202:205], v[16:19]
	v_mfma_f32_16x16x32_bf16 v[4:7], v[170:173], v[236:239], v[4:7]
	v_mfma_f32_16x16x32_bf16 v[0:3], v[178:181], v[236:239], v[0:3]
	v_mfma_f32_16x16x32_bf16 v[52:55], v[174:177], v[190:193], v[52:55]
	v_mfma_f32_16x16x32_bf16 v[48:51], v[182:185], v[190:193], v[48:51]
	v_mfma_f32_16x16x32_bf16 v[36:39], v[174:177], v[198:201], v[36:39]
	v_mfma_f32_16x16x32_bf16 v[32:35], v[182:185], v[198:201], v[32:35]
	v_mfma_f32_16x16x32_bf16 v[20:23], v[174:177], v[222:225], v[20:23]
	v_mfma_f32_16x16x32_bf16 v[16:19], v[182:185], v[222:225], v[16:19]
	v_mfma_f32_16x16x32_bf16 v[4:7], v[174:177], v[240:243], v[4:7]
	v_mfma_f32_16x16x32_bf16 v[0:3], v[182:185], v[240:243], v[0:3]
	s_setprio 0
	s_barrier
	s_add_i32 s35, 0, 0x18000
	v_add_u32_e32 v146, s35, v139
	s_add_i32 s92, 0, 0x1c000
	ds_read_b128 v[148:151], v146
	ds_read_b128 v[152:155], v146 offset:1024
	ds_read_b128 v[156:159], v146 offset:2048
	ds_read_b128 v[160:163], v146 offset:3072
	v_add_u32_e32 v146, s92, v139
	ds_read_b128 v[170:173], v146
	ds_read_b128 v[174:177], v146 offset:1024
	ds_read_b128 v[178:181], v146 offset:2048
	ds_read_b128 v[182:185], v146 offset:3072
	s_add_u32 s10, s10, 0x40000
	s_addc_u32 s11, s11, 0
	s_mov_b32 m0, s42
	ds_read_b128 v[186:189], v168 offset:32768
	ds_read_b128 v[190:193], v168 offset:33792
	ds_read_b128 v[194:197], v168 offset:34816
	ds_read_b128 v[198:201], v168 offset:35840
	ds_read_b128 v[202:205], v168 offset:36864
	ds_read_b128 v[222:225], v168 offset:37888
	ds_read_b128 v[236:239], v168 offset:38912
	ds_read_b128 v[240:243], v168 offset:39936
	global_load_lds_dwordx4 v134, s[10:11]
	s_mov_b32 m0, s43
	s_nop 0
	global_load_lds_dwordx4 v130, s[10:11]
	s_waitcnt vmcnt(8)
	s_waitcnt lgkmcnt(0)
	s_barrier
	s_setprio 1
	s_waitcnt lgkmcnt(0)
	v_mfma_f32_16x16x32_bf16 v[124:127], v[148:151], v[186:189], v[124:127]
	v_mfma_f32_16x16x32_bf16 v[120:123], v[156:159], v[186:189], v[120:123]
	v_mfma_f32_16x16x32_bf16 v[108:111], v[148:151], v[194:197], v[108:111]
	v_mfma_f32_16x16x32_bf16 v[104:107], v[156:159], v[194:197], v[104:107]
	v_mfma_f32_16x16x32_bf16 v[92:95], v[148:151], v[202:205], v[92:95]
	v_mfma_f32_16x16x32_bf16 v[88:91], v[156:159], v[202:205], v[88:91]
	v_mfma_f32_16x16x32_bf16 v[76:79], v[148:151], v[236:239], v[76:79]
	v_mfma_f32_16x16x32_bf16 v[72:75], v[156:159], v[236:239], v[72:75]
	v_mfma_f32_16x16x32_bf16 v[124:127], v[152:155], v[190:193], v[124:127]
	v_mfma_f32_16x16x32_bf16 v[120:123], v[160:163], v[190:193], v[120:123]
	v_mfma_f32_16x16x32_bf16 v[108:111], v[152:155], v[198:201], v[108:111]
	v_mfma_f32_16x16x32_bf16 v[104:107], v[160:163], v[198:201], v[104:107]
	v_mfma_f32_16x16x32_bf16 v[92:95], v[152:155], v[222:225], v[92:95]
	v_mfma_f32_16x16x32_bf16 v[88:91], v[160:163], v[222:225], v[88:91]
	v_mfma_f32_16x16x32_bf16 v[76:79], v[152:155], v[240:243], v[76:79]
	v_mfma_f32_16x16x32_bf16 v[72:75], v[160:163], v[240:243], v[72:75]
	s_setprio 0
	s_setprio 1
	v_mfma_f32_16x16x32_bf16 v[116:119], v[170:173], v[186:189], v[116:119]
	v_mfma_f32_16x16x32_bf16 v[112:115], v[178:181], v[186:189], v[112:115]
	v_mfma_f32_16x16x32_bf16 v[100:103], v[170:173], v[194:197], v[100:103]
	v_mfma_f32_16x16x32_bf16 v[96:99], v[178:181], v[194:197], v[96:99]
	v_mfma_f32_16x16x32_bf16 v[84:87], v[170:173], v[202:205], v[84:87]
	v_mfma_f32_16x16x32_bf16 v[80:83], v[178:181], v[202:205], v[80:83]
	v_mfma_f32_16x16x32_bf16 v[68:71], v[170:173], v[236:239], v[68:71]
	v_mfma_f32_16x16x32_bf16 v[64:67], v[178:181], v[236:239], v[64:67]
	v_mfma_f32_16x16x32_bf16 v[116:119], v[174:177], v[190:193], v[116:119]
	v_mfma_f32_16x16x32_bf16 v[112:115], v[182:185], v[190:193], v[112:115]
	v_mfma_f32_16x16x32_bf16 v[100:103], v[174:177], v[198:201], v[100:103]
	v_mfma_f32_16x16x32_bf16 v[96:99], v[182:185], v[198:201], v[96:99]
	v_mfma_f32_16x16x32_bf16 v[84:87], v[174:177], v[222:225], v[84:87]
	v_mfma_f32_16x16x32_bf16 v[80:83], v[182:185], v[222:225], v[80:83]
	v_mfma_f32_16x16x32_bf16 v[68:71], v[174:177], v[240:243], v[68:71]
	v_mfma_f32_16x16x32_bf16 v[64:67], v[182:185], v[240:243], v[64:67]
	s_setprio 0
	s_barrier
	s_add_i32 s10, s35, s37
	v_lshl_add_u64 v[206:207], v[206:207], 0, s[94:95]
	s_mov_b32 m0, s10
	ds_read_b128 v[186:189], v168 offset:49152
	ds_read_b128 v[190:193], v168 offset:50176
	ds_read_b128 v[194:197], v168 offset:51200
	ds_read_b128 v[198:201], v168 offset:52224
	ds_read_b128 v[202:205], v168 offset:53248
	ds_read_b128 v[222:225], v168 offset:54272
	ds_read_b128 v[236:239], v168 offset:55296
	ds_read_b128 v[240:243], v168 offset:56320
	global_load_lds_dwordx4 v[206:207], off
	s_add_i32 m0, s10, 0x2000
	s_add_u32 s6, s6, 0x40080
	v_lshl_add_u64 v[206:207], v[244:245], 0, s[94:95]
	s_addc_u32 s7, s7, 0
	s_add_i32 s10, s92, s37
	global_load_lds_dwordx4 v[206:207], off
	s_mov_b32 m0, s10
	s_nop 0
	global_load_lds_dwordx4 v132, s[6:7]
	v_lshl_add_u64 v[206:207], s[6:7], 0, v[128:129]
	s_add_i32 m0, s10, 0x2000
	s_nop 0
	global_load_lds_dwordx4 v[206:207], off
	v_lshl_add_u64 v[206:207], v[246:247], 0, s[94:95]
	s_mov_b32 m0, s76
	s_nop 0
	global_load_lds_dwordx4 v[206:207], off
	v_lshl_add_u64 v[206:207], v[248:249], 0, s[94:95]
	s_mov_b32 m0, s77
	s_nop 0
	global_load_lds_dwordx4 v[206:207], off
	s_waitcnt vmcnt(8)
	s_waitcnt lgkmcnt(0)
	s_barrier
	s_setprio 1
	s_waitcnt lgkmcnt(0)
	v_mfma_f32_16x16x32_bf16 v[60:63], v[148:151], v[186:189], v[60:63]
	v_mfma_f32_16x16x32_bf16 v[56:59], v[156:159], v[186:189], v[56:59]
	v_mfma_f32_16x16x32_bf16 v[44:47], v[148:151], v[194:197], v[44:47]
	v_mfma_f32_16x16x32_bf16 v[40:43], v[156:159], v[194:197], v[40:43]
	v_mfma_f32_16x16x32_bf16 v[28:31], v[148:151], v[202:205], v[28:31]
	v_mfma_f32_16x16x32_bf16 v[24:27], v[156:159], v[202:205], v[24:27]
	v_mfma_f32_16x16x32_bf16 v[12:15], v[148:151], v[236:239], v[12:15]
	v_mfma_f32_16x16x32_bf16 v[8:11], v[156:159], v[236:239], v[8:11]
	v_mfma_f32_16x16x32_bf16 v[60:63], v[152:155], v[190:193], v[60:63]
	v_mfma_f32_16x16x32_bf16 v[56:59], v[160:163], v[190:193], v[56:59]
	v_mfma_f32_16x16x32_bf16 v[44:47], v[152:155], v[198:201], v[44:47]
	v_mfma_f32_16x16x32_bf16 v[40:43], v[160:163], v[198:201], v[40:43]
	v_mfma_f32_16x16x32_bf16 v[28:31], v[152:155], v[222:225], v[28:31]
	v_mfma_f32_16x16x32_bf16 v[24:27], v[160:163], v[222:225], v[24:27]
	v_mfma_f32_16x16x32_bf16 v[12:15], v[152:155], v[240:243], v[12:15]
	v_mfma_f32_16x16x32_bf16 v[8:11], v[160:163], v[240:243], v[8:11]
	s_setprio 0
	s_setprio 1
	v_mfma_f32_16x16x32_bf16 v[52:55], v[170:173], v[186:189], v[52:55]
	v_mfma_f32_16x16x32_bf16 v[48:51], v[178:181], v[186:189], v[48:51]
	v_mfma_f32_16x16x32_bf16 v[36:39], v[170:173], v[194:197], v[36:39]
	v_mfma_f32_16x16x32_bf16 v[32:35], v[178:181], v[194:197], v[32:35]
	v_mfma_f32_16x16x32_bf16 v[20:23], v[170:173], v[202:205], v[20:23]
	v_mfma_f32_16x16x32_bf16 v[16:19], v[178:181], v[202:205], v[16:19]
	v_mfma_f32_16x16x32_bf16 v[4:7], v[170:173], v[236:239], v[4:7]
	v_mfma_f32_16x16x32_bf16 v[0:3], v[178:181], v[236:239], v[0:3]
	v_mfma_f32_16x16x32_bf16 v[52:55], v[174:177], v[190:193], v[52:55]
	v_mfma_f32_16x16x32_bf16 v[48:51], v[182:185], v[190:193], v[48:51]
	v_mfma_f32_16x16x32_bf16 v[36:39], v[174:177], v[198:201], v[36:39]
	v_mfma_f32_16x16x32_bf16 v[32:35], v[182:185], v[198:201], v[32:35]
	v_mfma_f32_16x16x32_bf16 v[20:23], v[174:177], v[222:225], v[20:23]
	v_mfma_f32_16x16x32_bf16 v[16:19], v[182:185], v[222:225], v[16:19]
	v_mfma_f32_16x16x32_bf16 v[4:7], v[174:177], v[240:243], v[4:7]
	v_mfma_f32_16x16x32_bf16 v[0:3], v[182:185], v[240:243], v[0:3]
	s_setprio 0
	s_barrier
	s_add_i32 s34, s34, 2
	s_add_u32 s4, s4, 0x100
	s_addc_u32 s5, s5, 0
	s_add_u32 s28, s28, 0x100
	s_addc_u32 s29, s29, 0
	s_cmp_gt_u32 s34, 13
	s_cbranch_scc0 .LBB0_260
	v_and_b32_e32 v148, 15, v226
	v_bfe_u32 v149, v226, 4, 2
	v_bfe_u32 v150, v226, 6, 2
	v_lshrrev_b32_e32 v151, 8, v226
	v_lshl_add_u32 v152, v151, 6, v148
	v_lshlrev_b32_e32 v153, 2, v152
	s_lshl_b32 s4, s31, 10
	s_add_u32 s100, s96, s4
	s_addc_u32 s101, s97, 0
	global_load_dword v154, v153, s[100:101]
	global_load_dword v155, v153, s[100:101] offset:64
	global_load_dword v156, v153, s[100:101] offset:128
	global_load_dword v157, v153, s[100:101] offset:192
	global_load_dword v158, v153, s[100:101] offset:512
	global_load_dword v159, v153, s[100:101] offset:576
	global_load_dword v160, v153, s[100:101] offset:640
	global_load_dword v161, v153, s[100:101] offset:704
	s_and_b64 vcc, exec, s[16:17]
	s_cbranch_vccz .LBB0_263
	s_barrier

.LBB0_710:
	s_add_u32 s24, s22, 0xfffc0080
	s_addc_u32 s25, s23, -1
	s_add_i32 vcc_lo, 0, 0x10000
	s_cmp_eq_u32 s92, 12
	s_cselect_b32 s27, s17, s25
	s_cselect_b32 s26, s70, s24
	v_add_u32_e32 v142, vcc_lo, v145
	s_cselect_b32 s25, s15, s83
	s_cselect_b32 s24, s80, s82
	s_add_i32 s10, 0, 0x14000
	ds_read_b128 v[138:141], v142
	ds_read_b128 v[148:151], v142 offset:1024
	ds_read_b128 v[152:155], v142 offset:2048
	ds_read_b128 v[156:159], v142 offset:3072
	v_add_u32_e32 v142, s10, v145
	ds_read_b128 v[160:163], v142
	ds_read_b128 v[164:167], v142 offset:1024
	ds_read_b128 v[168:171], v142 offset:2048
	ds_read_b128 v[172:175], v142 offset:3072
	s_add_i32 m0, s31, 0xc000
	ds_read_b128 v[176:179], v147
	ds_read_b128 v[180:183], v147 offset:1024
	ds_read_b128 v[184:187], v147 offset:2048
	ds_read_b128 v[188:191], v147 offset:3072
	ds_read_b128 v[192:195], v147 offset:4096
	ds_read_b128 v[196:199], v147 offset:5120
	ds_read_b128 v[200:203], v147 offset:6144
	ds_read_b128 v[204:207], v147 offset:7168
	global_load_lds_dwordx4 v134, s[22:23]
	s_add_i32 m0, s31, 0xe000
	s_nop 0
	global_load_lds_dwordx4 v136, s[22:23]
	s_waitcnt vmcnt(8)
	s_waitcnt lgkmcnt(0)
	s_barrier
	s_setprio 1
	s_waitcnt lgkmcnt(0)
	v_mfma_f32_16x16x32_bf16 v[124:127], v[138:141], v[176:179], v[124:127]
	v_mfma_f32_16x16x32_bf16 v[120:123], v[152:155], v[176:179], v[120:123]
	v_mfma_f32_16x16x32_bf16 v[108:111], v[138:141], v[184:187], v[108:111]
	v_mfma_f32_16x16x32_bf16 v[104:107], v[152:155], v[184:187], v[104:107]
	v_mfma_f32_16x16x32_bf16 v[92:95], v[138:141], v[192:195], v[92:95]
	v_mfma_f32_16x16x32_bf16 v[88:91], v[152:155], v[192:195], v[88:91]
	v_mfma_f32_16x16x32_bf16 v[76:79], v[138:141], v[200:203], v[76:79]
	v_mfma_f32_16x16x32_bf16 v[72:75], v[152:155], v[200:203], v[72:75]
	v_mfma_f32_16x16x32_bf16 v[124:127], v[148:151], v[180:183], v[124:127]
	v_mfma_f32_16x16x32_bf16 v[120:123], v[156:159], v[180:183], v[120:123]
	v_mfma_f32_16x16x32_bf16 v[108:111], v[148:151], v[188:191], v[108:111]
	v_mfma_f32_16x16x32_bf16 v[104:107], v[156:159], v[188:191], v[104:107]
	v_mfma_f32_16x16x32_bf16 v[92:95], v[148:151], v[196:199], v[92:95]
	v_mfma_f32_16x16x32_bf16 v[88:91], v[156:159], v[196:199], v[88:91]
	v_mfma_f32_16x16x32_bf16 v[76:79], v[148:151], v[204:207], v[76:79]
	v_mfma_f32_16x16x32_bf16 v[72:75], v[156:159], v[204:207], v[72:75]
	s_setprio 0
	s_setprio 1
	v_mfma_f32_16x16x32_bf16 v[116:119], v[160:163], v[176:179], v[116:119]
	v_mfma_f32_16x16x32_bf16 v[112:115], v[168:171], v[176:179], v[112:115]
	v_mfma_f32_16x16x32_bf16 v[100:103], v[160:163], v[184:187], v[100:103]
	v_mfma_f32_16x16x32_bf16 v[96:99], v[168:171], v[184:187], v[96:99]
	v_mfma_f32_16x16x32_bf16 v[84:87], v[160:163], v[192:195], v[84:87]
	v_mfma_f32_16x16x32_bf16 v[80:83], v[168:171], v[192:195], v[80:83]
	v_mfma_f32_16x16x32_bf16 v[68:71], v[160:163], v[200:203], v[68:71]
	v_mfma_f32_16x16x32_bf16 v[64:67], v[168:171], v[200:203], v[64:67]
	v_mfma_f32_16x16x32_bf16 v[116:119], v[164:167], v[180:183], v[116:119]
	v_mfma_f32_16x16x32_bf16 v[112:115], v[172:175], v[180:183], v[112:115]
	v_mfma_f32_16x16x32_bf16 v[100:103], v[164:167], v[188:191], v[100:103]
	v_mfma_f32_16x16x32_bf16 v[96:99], v[172:175], v[188:191], v[96:99]
	v_mfma_f32_16x16x32_bf16 v[84:87], v[164:167], v[196:199], v[84:87]
	v_mfma_f32_16x16x32_bf16 v[80:83], v[172:175], v[196:199], v[80:83]
	v_mfma_f32_16x16x32_bf16 v[68:71], v[164:167], v[204:207], v[68:71]
	v_mfma_f32_16x16x32_bf16 v[64:67], v[172:175], v[204:207], v[64:67]
	s_setprio 0
	s_barrier
	s_add_i32 s11, vcc_lo, s30
	v_lshl_add_u64 v[142:143], s[24:25], 0, v[208:209]
	s_mov_b32 m0, s11
	ds_read_b128 v[176:179], v147 offset:16384
	ds_read_b128 v[180:183], v147 offset:17408
	ds_read_b128 v[184:187], v147 offset:18432
	ds_read_b128 v[188:191], v147 offset:19456
	ds_read_b128 v[192:195], v147 offset:20480
	ds_read_b128 v[196:199], v147 offset:21504
	ds_read_b128 v[200:203], v147 offset:22528
	ds_read_b128 v[204:207], v147 offset:23552
	global_load_lds_dwordx4 v[142:143], off
	s_add_i32 m0, s11, 0x2000
	s_add_u32 vcc_lo, s24, 0x40000
	v_lshl_add_u64 v[222:223], s[24:25], 0, v[128:129]
	s_addc_u32 vcc_hi, s25, 0
	s_add_i32 s10, s10, s30
	global_load_lds_dwordx4 v[222:223], off
	s_mov_b32 m0, s10
	v_lshl_add_u64 v[236:237], s[26:27], 0, v[130:131]
	global_load_lds_dwordx4 v208, vcc
	s_add_i32 m0, s10, 0x2000
	s_nop 0
	global_load_lds_dwordx4 v128, vcc
	v_lshl_add_u64 v[224:225], s[26:27], 0, v[132:133]
	s_mov_b32 m0, s31
	s_nop 0
	global_load_lds_dwordx4 v[224:225], off
	s_mov_b32 m0, s34
	s_nop 0
	global_load_lds_dwordx4 v[236:237], off
	s_waitcnt vmcnt(8)
	s_waitcnt lgkmcnt(0)
	s_barrier
	s_setprio 1
	s_waitcnt lgkmcnt(0)
	v_mfma_f32_16x16x32_bf16 v[60:63], v[138:141], v[176:179], v[60:63]
	v_mfma_f32_16x16x32_bf16 v[56:59], v[152:155], v[176:179], v[56:59]
	v_mfma_f32_16x16x32_bf16 v[44:47], v[138:141], v[184:187], v[44:47]
	v_mfma_f32_16x16x32_bf16 v[40:43], v[152:155], v[184:187], v[40:43]
	v_mfma_f32_16x16x32_bf16 v[28:31], v[138:141], v[192:195], v[28:31]
	v_mfma_f32_16x16x32_bf16 v[24:27], v[152:155], v[192:195], v[24:27]
	v_mfma_f32_16x16x32_bf16 v[12:15], v[138:141], v[200:203], v[12:15]
	v_mfma_f32_16x16x32_bf16 v[8:11], v[152:155], v[200:203], v[8:11]
	v_mfma_f32_16x16x32_bf16 v[60:63], v[148:151], v[180:183], v[60:63]
	v_mfma_f32_16x16x32_bf16 v[56:59], v[156:159], v[180:183], v[56:59]
	v_mfma_f32_16x16x32_bf16 v[44:47], v[148:151], v[188:191], v[44:47]
	v_mfma_f32_16x16x32_bf16 v[40:43], v[156:159], v[188:191], v[40:43]
	v_mfma_f32_16x16x32_bf16 v[28:31], v[148:151], v[196:199], v[28:31]
	v_mfma_f32_16x16x32_bf16 v[24:27], v[156:159], v[196:199], v[24:27]
	v_mfma_f32_16x16x32_bf16 v[12:15], v[148:151], v[204:207], v[12:15]
	v_mfma_f32_16x16x32_bf16 v[8:11], v[156:159], v[204:207], v[8:11]
	s_setprio 0
	s_setprio 1
	v_mfma_f32_16x16x32_bf16 v[52:55], v[160:163], v[176:179], v[52:55]
	v_mfma_f32_16x16x32_bf16 v[48:51], v[168:171], v[176:179], v[48:51]
	v_mfma_f32_16x16x32_bf16 v[36:39], v[160:163], v[184:187], v[36:39]
	v_mfma_f32_16x16x32_bf16 v[32:35], v[168:171], v[184:187], v[32:35]
	v_mfma_f32_16x16x32_bf16 v[20:23], v[160:163], v[192:195], v[20:23]
	v_mfma_f32_16x16x32_bf16 v[16:19], v[168:171], v[192:195], v[16:19]
	v_mfma_f32_16x16x32_bf16 v[4:7], v[160:163], v[200:203], v[4:7]
	v_mfma_f32_16x16x32_bf16 v[0:3], v[168:171], v[200:203], v[0:3]
	v_mfma_f32_16x16x32_bf16 v[52:55], v[164:167], v[180:183], v[52:55]
	v_mfma_f32_16x16x32_bf16 v[48:51], v[172:175], v[180:183], v[48:51]
	v_mfma_f32_16x16x32_bf16 v[36:39], v[164:167], v[188:191], v[36:39]
	v_mfma_f32_16x16x32_bf16 v[32:35], v[172:175], v[188:191], v[32:35]
	v_mfma_f32_16x16x32_bf16 v[20:23], v[164:167], v[196:199], v[20:23]
	v_mfma_f32_16x16x32_bf16 v[16:19], v[172:175], v[196:199], v[16:19]
	v_mfma_f32_16x16x32_bf16 v[4:7], v[164:167], v[204:207], v[4:7]
	v_mfma_f32_16x16x32_bf16 v[0:3], v[172:175], v[204:207], v[0:3]
	s_setprio 0
	s_barrier
	s_add_i32 s10, 0, 0x18000
	s_add_i32 s11, 0, 0x1c000
	v_add_u32_e32 v156, s10, v145
	v_add_u32_e32 v172, s11, v145
	ds_read_b128 v[138:141], v156
	ds_read_b128 v[148:151], v156 offset:1024
	ds_read_b128 v[152:155], v156 offset:2048
	ds_read_b128 v[156:159], v156 offset:3072
	ds_read_b128 v[160:163], v172
	ds_read_b128 v[164:167], v172 offset:1024
	ds_read_b128 v[168:171], v172 offset:2048
	ds_read_b128 v[172:175], v172 offset:3072
	s_add_u32 s26, s26, 0x40000
	s_addc_u32 s27, s27, 0
	s_mov_b32 m0, s35
	ds_read_b128 v[176:179], v147 offset:32768
	ds_read_b128 v[180:183], v147 offset:33792
	ds_read_b128 v[184:187], v147 offset:34816
	ds_read_b128 v[188:191], v147 offset:35840
	ds_read_b128 v[192:195], v147 offset:36864
	ds_read_b128 v[196:199], v147 offset:37888
	ds_read_b128 v[200:203], v147 offset:38912
	ds_read_b128 v[204:207], v147 offset:39936
	global_load_lds_dwordx4 v132, s[26:27]
	s_mov_b32 m0, s36
	s_nop 0
	global_load_lds_dwordx4 v130, s[26:27]
	s_waitcnt vmcnt(8)
	s_waitcnt lgkmcnt(0)
	s_barrier
	s_setprio 1
	s_waitcnt lgkmcnt(0)
	v_mfma_f32_16x16x32_bf16 v[124:127], v[138:141], v[176:179], v[124:127]
	v_mfma_f32_16x16x32_bf16 v[120:123], v[152:155], v[176:179], v[120:123]
	v_mfma_f32_16x16x32_bf16 v[108:111], v[138:141], v[184:187], v[108:111]
	v_mfma_f32_16x16x32_bf16 v[104:107], v[152:155], v[184:187], v[104:107]
	v_mfma_f32_16x16x32_bf16 v[92:95], v[138:141], v[192:195], v[92:95]
	v_mfma_f32_16x16x32_bf16 v[88:91], v[152:155], v[192:195], v[88:91]
	v_mfma_f32_16x16x32_bf16 v[76:79], v[138:141], v[200:203], v[76:79]
	v_mfma_f32_16x16x32_bf16 v[72:75], v[152:155], v[200:203], v[72:75]
	v_mfma_f32_16x16x32_bf16 v[124:127], v[148:151], v[180:183], v[124:127]
	v_mfma_f32_16x16x32_bf16 v[120:123], v[156:159], v[180:183], v[120:123]
	v_mfma_f32_16x16x32_bf16 v[108:111], v[148:151], v[188:191], v[108:111]
	v_mfma_f32_16x16x32_bf16 v[104:107], v[156:159], v[188:191], v[104:107]
	v_mfma_f32_16x16x32_bf16 v[92:95], v[148:151], v[196:199], v[92:95]
	v_mfma_f32_16x16x32_bf16 v[88:91], v[156:159], v[196:199], v[88:91]
	v_mfma_f32_16x16x32_bf16 v[76:79], v[148:151], v[204:207], v[76:79]
	v_mfma_f32_16x16x32_bf16 v[72:75], v[156:159], v[204:207], v[72:75]
	s_setprio 0
	s_setprio 1
	v_mfma_f32_16x16x32_bf16 v[116:119], v[160:163], v[176:179], v[116:119]
	v_mfma_f32_16x16x32_bf16 v[112:115], v[168:171], v[176:179], v[112:115]
	v_mfma_f32_16x16x32_bf16 v[100:103], v[160:163], v[184:187], v[100:103]
	v_mfma_f32_16x16x32_bf16 v[96:99], v[168:171], v[184:187], v[96:99]
	v_mfma_f32_16x16x32_bf16 v[84:87], v[160:163], v[192:195], v[84:87]
	v_mfma_f32_16x16x32_bf16 v[80:83], v[168:171], v[192:195], v[80:83]
	v_mfma_f32_16x16x32_bf16 v[68:71], v[160:163], v[200:203], v[68:71]
	v_mfma_f32_16x16x32_bf16 v[64:67], v[168:171], v[200:203], v[64:67]
	v_mfma_f32_16x16x32_bf16 v[116:119], v[164:167], v[180:183], v[116:119]
	v_mfma_f32_16x16x32_bf16 v[112:115], v[172:175], v[180:183], v[112:115]
	v_mfma_f32_16x16x32_bf16 v[100:103], v[164:167], v[188:191], v[100:103]
	v_mfma_f32_16x16x32_bf16 v[96:99], v[172:175], v[188:191], v[96:99]
	v_mfma_f32_16x16x32_bf16 v[84:87], v[164:167], v[196:199], v[84:87]
	v_mfma_f32_16x16x32_bf16 v[80:83], v[172:175], v[196:199], v[80:83]
	v_mfma_f32_16x16x32_bf16 v[68:71], v[164:167], v[204:207], v[68:71]
	v_mfma_f32_16x16x32_bf16 v[64:67], v[172:175], v[204:207], v[64:67]
	s_setprio 0
	s_barrier
	s_add_i32 s10, s10, s30
	v_lshl_add_u64 v[142:143], v[142:143], 0, s[94:95]
	s_mov_b32 m0, s10
	ds_read_b128 v[176:179], v147 offset:49152
	ds_read_b128 v[180:183], v147 offset:50176
	ds_read_b128 v[184:187], v147 offset:51200
	ds_read_b128 v[188:191], v147 offset:52224
	ds_read_b128 v[192:195], v147 offset:53248
	ds_read_b128 v[196:199], v147 offset:54272
	ds_read_b128 v[200:203], v147 offset:55296
	ds_read_b128 v[204:207], v147 offset:56320
	global_load_lds_dwordx4 v[142:143], off
	s_add_i32 m0, s10, 0x2000
	s_add_u32 s24, s24, 0x40080
	v_lshl_add_u64 v[142:143], v[222:223], 0, s[94:95]
	s_addc_u32 s25, s25, 0
	s_add_i32 s10, s11, s30
	global_load_lds_dwordx4 v[142:143], off
	s_mov_b32 m0, s10
	s_nop 0
	global_load_lds_dwordx4 v208, s[24:25]
	v_lshl_add_u64 v[142:143], s[24:25], 0, v[128:129]
	s_add_i32 m0, s10, 0x2000
	s_nop 0
	global_load_lds_dwordx4 v[142:143], off
	v_lshl_add_u64 v[142:143], v[224:225], 0, s[94:95]
	s_mov_b32 m0, s37
	s_nop 0
	global_load_lds_dwordx4 v[142:143], off
	v_lshl_add_u64 v[142:143], v[236:237], 0, s[94:95]
	s_mov_b32 m0, s40
	s_nop 0
	global_load_lds_dwordx4 v[142:143], off
	s_waitcnt vmcnt(8)
	s_waitcnt lgkmcnt(0)
	s_barrier
	s_setprio 1
	s_waitcnt lgkmcnt(0)
	v_mfma_f32_16x16x32_bf16 v[60:63], v[138:141], v[176:179], v[60:63]
	v_mfma_f32_16x16x32_bf16 v[56:59], v[152:155], v[176:179], v[56:59]
	v_mfma_f32_16x16x32_bf16 v[44:47], v[138:141], v[184:187], v[44:47]
	v_mfma_f32_16x16x32_bf16 v[40:43], v[152:155], v[184:187], v[40:43]
	v_mfma_f32_16x16x32_bf16 v[28:31], v[138:141], v[192:195], v[28:31]
	v_mfma_f32_16x16x32_bf16 v[24:27], v[152:155], v[192:195], v[24:27]
	v_mfma_f32_16x16x32_bf16 v[12:15], v[138:141], v[200:203], v[12:15]
	v_mfma_f32_16x16x32_bf16 v[8:11], v[152:155], v[200:203], v[8:11]
	v_mfma_f32_16x16x32_bf16 v[60:63], v[148:151], v[180:183], v[60:63]
	v_mfma_f32_16x16x32_bf16 v[56:59], v[156:159], v[180:183], v[56:59]
	v_mfma_f32_16x16x32_bf16 v[44:47], v[148:151], v[188:191], v[44:47]
	v_mfma_f32_16x16x32_bf16 v[40:43], v[156:159], v[188:191], v[40:43]
	v_mfma_f32_16x16x32_bf16 v[28:31], v[148:151], v[196:199], v[28:31]
	v_mfma_f32_16x16x32_bf16 v[24:27], v[156:159], v[196:199], v[24:27]
	v_mfma_f32_16x16x32_bf16 v[12:15], v[148:151], v[204:207], v[12:15]
	v_mfma_f32_16x16x32_bf16 v[8:11], v[156:159], v[204:207], v[8:11]
	s_setprio 0
	s_setprio 1
	v_mfma_f32_16x16x32_bf16 v[52:55], v[160:163], v[176:179], v[52:55]
	v_mfma_f32_16x16x32_bf16 v[48:51], v[168:171], v[176:179], v[48:51]
	v_mfma_f32_16x16x32_bf16 v[36:39], v[160:163], v[184:187], v[36:39]
	v_mfma_f32_16x16x32_bf16 v[32:35], v[168:171], v[184:187], v[32:35]
	v_mfma_f32_16x16x32_bf16 v[20:23], v[160:163], v[192:195], v[20:23]
	v_mfma_f32_16x16x32_bf16 v[16:19], v[168:171], v[192:195], v[16:19]
	v_mfma_f32_16x16x32_bf16 v[4:7], v[160:163], v[200:203], v[4:7]
	v_mfma_f32_16x16x32_bf16 v[0:3], v[168:171], v[200:203], v[0:3]
	v_mfma_f32_16x16x32_bf16 v[52:55], v[164:167], v[180:183], v[52:55]
	v_mfma_f32_16x16x32_bf16 v[48:51], v[172:175], v[180:183], v[48:51]
	v_mfma_f32_16x16x32_bf16 v[36:39], v[164:167], v[188:191], v[36:39]
	v_mfma_f32_16x16x32_bf16 v[32:35], v[172:175], v[188:191], v[32:35]
	v_mfma_f32_16x16x32_bf16 v[20:23], v[164:167], v[196:199], v[20:23]
	v_mfma_f32_16x16x32_bf16 v[16:19], v[172:175], v[196:199], v[16:19]
	v_mfma_f32_16x16x32_bf16 v[4:7], v[164:167], v[204:207], v[4:7]
	v_mfma_f32_16x16x32_bf16 v[0:3], v[172:175], v[204:207], v[0:3]
	s_setprio 0
	s_barrier
	s_add_i32 s92, s92, 2
	s_add_u32 s22, s22, 0x100
	s_addc_u32 s23, s23, 0
	s_add_u32 s82, s82, 0x100
	s_addc_u32 s83, s83, 0
	s_cmp_gt_u32 s92, 13
	s_cbranch_scc0 .LBB0_710
	v_lshl_add_u32 v140, s43, 8, v144
	v_lshl_or_b32 v138, s42, 8, v146
	v_lshlrev_b32_e32 v139, 2, v140
	v_lshlrev_b32_e32 v140, 11, v140
	v_lshl_add_u32 v138, v138, 1, v140
	s_mov_b64 s[100:101], s[46:47]
	global_load_dwordx4 v[148:151], v138, s[100:101]
	global_load_dwordx4 v[152:155], v138, s[100:101] offset:256
	s_add_u32 s100, s100, 0x8000
	s_addc_u32 s101, s101, 0
	global_load_dwordx4 v[156:159], v138, s[100:101]
	global_load_dwordx4 v[160:163], v138, s[100:101] offset:256
	s_add_u32 s100, s100, 0x8000
	s_addc_u32 s101, s101, 0
	global_load_dwordx4 v[164:167], v138, s[100:101]
	global_load_dwordx4 v[168:171], v138, s[100:101] offset:256
	s_add_u32 s100, s100, 0x8000
	s_addc_u32 s101, s101, 0
	global_load_dwordx4 v[172:175], v138, s[100:101]
	global_load_dwordx4 v[176:179], v138, s[100:101] offset:256
	s_add_u32 s100, s100, 0x28000
	s_addc_u32 s101, s101, 0
	global_load_dwordx4 v[180:183], v138, s[100:101]
	global_load_dwordx4 v[184:187], v138, s[100:101] offset:256
	s_add_u32 s100, s100, 0x8000
	s_addc_u32 s101, s101, 0
	global_load_dwordx4 v[188:191], v138, s[100:101]
	global_load_dwordx4 v[192:195], v138, s[100:101] offset:256
	s_add_u32 s100, s100, 0x8000
	s_addc_u32 s101, s101, 0
	global_load_dwordx4 v[196:199], v138, s[100:101]
	global_load_dwordx4 v[200:203], v138, s[100:101] offset:256
	s_add_u32 s100, s100, 0x8000
	s_addc_u32 s101, s101, 0
	global_load_dwordx4 v[204:207], v138, s[100:101]
	global_load_dwordx4 v[236:239], v138, s[100:101] offset:256
	s_and_b64 vcc, exec, s[12:13]
	s_cbranch_vccz .LBB0_713
	s_barrier

.LBB0_795:
	s_add_u32 s10, s20, 0xfffc0080
	s_addc_u32 s11, s21, -1
	s_add_i32 s83, 0, 0x10000
	s_cmp_eq_u32 s82, 12
	s_cselect_b32 s25, s15, s11
	s_cselect_b32 s24, s42, s10
	v_add_u32_e32 v138, s83, v141
	s_cselect_b32 s23, s13, s80
	s_cselect_b32 s22, s43, s70
	s_add_i32 s10, 0, 0x14000
	ds_read_b128 v[144:147], v138
	ds_read_b128 v[148:151], v138 offset:1024
	ds_read_b128 v[152:155], v138 offset:2048
	ds_read_b128 v[156:159], v138 offset:3072
	v_add_u32_e32 v138, s10, v141
	ds_read_b128 v[160:163], v138
	ds_read_b128 v[164:167], v138 offset:1024
	ds_read_b128 v[168:171], v138 offset:2048
	ds_read_b128 v[172:175], v138 offset:3072
	s_add_i32 m0, s29, 0xc000
	ds_read_b128 v[176:179], v143
	ds_read_b128 v[180:183], v143 offset:1024
	ds_read_b128 v[184:187], v143 offset:2048
	ds_read_b128 v[188:191], v143 offset:3072
	ds_read_b128 v[192:195], v143 offset:4096
	ds_read_b128 v[196:199], v143 offset:5120
	ds_read_b128 v[200:203], v143 offset:6144
	ds_read_b128 v[204:207], v143 offset:7168
	global_load_lds_dwordx4 v134, s[20:21]
	s_add_i32 m0, s29, 0xe000
	s_nop 0
	global_load_lds_dwordx4 v136, s[20:21]
	s_waitcnt vmcnt(8)
	s_waitcnt lgkmcnt(0)
	s_barrier
	s_setprio 1
	s_waitcnt lgkmcnt(0)
	v_mfma_f32_16x16x32_bf16 v[124:127], v[144:147], v[176:179], v[124:127]
	v_mfma_f32_16x16x32_bf16 v[120:123], v[152:155], v[176:179], v[120:123]
	v_mfma_f32_16x16x32_bf16 v[108:111], v[144:147], v[184:187], v[108:111]
	v_mfma_f32_16x16x32_bf16 v[104:107], v[152:155], v[184:187], v[104:107]
	v_mfma_f32_16x16x32_bf16 v[92:95], v[144:147], v[192:195], v[92:95]
	v_mfma_f32_16x16x32_bf16 v[88:91], v[152:155], v[192:195], v[88:91]
	v_mfma_f32_16x16x32_bf16 v[76:79], v[144:147], v[200:203], v[76:79]
	v_mfma_f32_16x16x32_bf16 v[72:75], v[152:155], v[200:203], v[72:75]
	v_mfma_f32_16x16x32_bf16 v[124:127], v[148:151], v[180:183], v[124:127]
	v_mfma_f32_16x16x32_bf16 v[120:123], v[156:159], v[180:183], v[120:123]
	v_mfma_f32_16x16x32_bf16 v[108:111], v[148:151], v[188:191], v[108:111]
	v_mfma_f32_16x16x32_bf16 v[104:107], v[156:159], v[188:191], v[104:107]
	v_mfma_f32_16x16x32_bf16 v[92:95], v[148:151], v[196:199], v[92:95]
	v_mfma_f32_16x16x32_bf16 v[88:91], v[156:159], v[196:199], v[88:91]
	v_mfma_f32_16x16x32_bf16 v[76:79], v[148:151], v[204:207], v[76:79]
	v_mfma_f32_16x16x32_bf16 v[72:75], v[156:159], v[204:207], v[72:75]
	s_setprio 0
	s_setprio 1
	v_mfma_f32_16x16x32_bf16 v[116:119], v[160:163], v[176:179], v[116:119]
	v_mfma_f32_16x16x32_bf16 v[112:115], v[168:171], v[176:179], v[112:115]
	v_mfma_f32_16x16x32_bf16 v[100:103], v[160:163], v[184:187], v[100:103]
	v_mfma_f32_16x16x32_bf16 v[96:99], v[168:171], v[184:187], v[96:99]
	v_mfma_f32_16x16x32_bf16 v[84:87], v[160:163], v[192:195], v[84:87]
	v_mfma_f32_16x16x32_bf16 v[80:83], v[168:171], v[192:195], v[80:83]
	v_mfma_f32_16x16x32_bf16 v[68:71], v[160:163], v[200:203], v[68:71]
	v_mfma_f32_16x16x32_bf16 v[64:67], v[168:171], v[200:203], v[64:67]
	v_mfma_f32_16x16x32_bf16 v[116:119], v[164:167], v[180:183], v[116:119]
	v_mfma_f32_16x16x32_bf16 v[112:115], v[172:175], v[180:183], v[112:115]
	v_mfma_f32_16x16x32_bf16 v[100:103], v[164:167], v[188:191], v[100:103]
	v_mfma_f32_16x16x32_bf16 v[96:99], v[172:175], v[188:191], v[96:99]
	v_mfma_f32_16x16x32_bf16 v[84:87], v[164:167], v[196:199], v[84:87]
	v_mfma_f32_16x16x32_bf16 v[80:83], v[172:175], v[196:199], v[80:83]
	v_mfma_f32_16x16x32_bf16 v[68:71], v[164:167], v[204:207], v[68:71]
	v_mfma_f32_16x16x32_bf16 v[64:67], v[172:175], v[204:207], v[64:67]
	s_setprio 0
	s_barrier
	s_add_i32 s11, s83, s28
	v_lshl_add_u64 v[138:139], s[22:23], 0, v[208:209]
	s_mov_b32 m0, s11
	ds_read_b128 v[176:179], v143 offset:16384
	ds_read_b128 v[180:183], v143 offset:17408
	ds_read_b128 v[184:187], v143 offset:18432
	ds_read_b128 v[188:191], v143 offset:19456
	ds_read_b128 v[192:195], v143 offset:20480
	ds_read_b128 v[196:199], v143 offset:21504
	ds_read_b128 v[200:203], v143 offset:22528
	ds_read_b128 v[204:207], v143 offset:23552
	global_load_lds_dwordx4 v[138:139], off
	s_add_i32 m0, s11, 0x2000
	s_add_u32 vcc_lo, s22, 0x40000
	v_lshl_add_u64 v[222:223], s[22:23], 0, v[128:129]
	s_addc_u32 vcc_hi, s23, 0
	s_add_i32 s10, s10, s28
	global_load_lds_dwordx4 v[222:223], off
	s_mov_b32 m0, s10
	v_lshl_add_u64 v[236:237], s[24:25], 0, v[130:131]
	global_load_lds_dwordx4 v208, vcc
	s_add_i32 m0, s10, 0x2000
	s_nop 0
	global_load_lds_dwordx4 v128, vcc
	v_lshl_add_u64 v[224:225], s[24:25], 0, v[132:133]
	s_mov_b32 m0, s29
	s_nop 0
	global_load_lds_dwordx4 v[224:225], off
	s_mov_b32 m0, s30
	s_nop 0
	global_load_lds_dwordx4 v[236:237], off
	s_waitcnt vmcnt(8)
	s_waitcnt lgkmcnt(0)
	s_barrier
	s_setprio 1
	s_waitcnt lgkmcnt(0)
	v_mfma_f32_16x16x32_bf16 v[60:63], v[144:147], v[176:179], v[60:63]
	v_mfma_f32_16x16x32_bf16 v[56:59], v[152:155], v[176:179], v[56:59]
	v_mfma_f32_16x16x32_bf16 v[44:47], v[144:147], v[184:187], v[44:47]
	v_mfma_f32_16x16x32_bf16 v[40:43], v[152:155], v[184:187], v[40:43]
	v_mfma_f32_16x16x32_bf16 v[28:31], v[144:147], v[192:195], v[28:31]
	v_mfma_f32_16x16x32_bf16 v[24:27], v[152:155], v[192:195], v[24:27]
	v_mfma_f32_16x16x32_bf16 v[12:15], v[144:147], v[200:203], v[12:15]
	v_mfma_f32_16x16x32_bf16 v[8:11], v[152:155], v[200:203], v[8:11]
	v_mfma_f32_16x16x32_bf16 v[60:63], v[148:151], v[180:183], v[60:63]
	v_mfma_f32_16x16x32_bf16 v[56:59], v[156:159], v[180:183], v[56:59]
	v_mfma_f32_16x16x32_bf16 v[44:47], v[148:151], v[188:191], v[44:47]
	v_mfma_f32_16x16x32_bf16 v[40:43], v[156:159], v[188:191], v[40:43]
	v_mfma_f32_16x16x32_bf16 v[28:31], v[148:151], v[196:199], v[28:31]
	v_mfma_f32_16x16x32_bf16 v[24:27], v[156:159], v[196:199], v[24:27]
	v_mfma_f32_16x16x32_bf16 v[12:15], v[148:151], v[204:207], v[12:15]
	v_mfma_f32_16x16x32_bf16 v[8:11], v[156:159], v[204:207], v[8:11]
	s_setprio 0
	s_setprio 1
	v_mfma_f32_16x16x32_bf16 v[52:55], v[160:163], v[176:179], v[52:55]
	v_mfma_f32_16x16x32_bf16 v[48:51], v[168:171], v[176:179], v[48:51]
	v_mfma_f32_16x16x32_bf16 v[36:39], v[160:163], v[184:187], v[36:39]
	v_mfma_f32_16x16x32_bf16 v[32:35], v[168:171], v[184:187], v[32:35]
	v_mfma_f32_16x16x32_bf16 v[20:23], v[160:163], v[192:195], v[20:23]
	v_mfma_f32_16x16x32_bf16 v[16:19], v[168:171], v[192:195], v[16:19]
	v_mfma_f32_16x16x32_bf16 v[4:7], v[160:163], v[200:203], v[4:7]
	v_mfma_f32_16x16x32_bf16 v[0:3], v[168:171], v[200:203], v[0:3]
	v_mfma_f32_16x16x32_bf16 v[52:55], v[164:167], v[180:183], v[52:55]
	v_mfma_f32_16x16x32_bf16 v[48:51], v[172:175], v[180:183], v[48:51]
	v_mfma_f32_16x16x32_bf16 v[36:39], v[164:167], v[188:191], v[36:39]
	v_mfma_f32_16x16x32_bf16 v[32:35], v[172:175], v[188:191], v[32:35]
	v_mfma_f32_16x16x32_bf16 v[20:23], v[164:167], v[196:199], v[20:23]
	v_mfma_f32_16x16x32_bf16 v[16:19], v[172:175], v[196:199], v[16:19]
	v_mfma_f32_16x16x32_bf16 v[4:7], v[164:167], v[204:207], v[4:7]
	v_mfma_f32_16x16x32_bf16 v[0:3], v[172:175], v[204:207], v[0:3]
	s_setprio 0
	s_barrier
	s_add_i32 s10, 0, 0x18000
	s_add_i32 s11, 0, 0x1c000
	v_add_u32_e32 v156, s10, v141
	v_add_u32_e32 v172, s11, v141
	ds_read_b128 v[144:147], v156
	ds_read_b128 v[148:151], v156 offset:1024
	ds_read_b128 v[152:155], v156 offset:2048
	ds_read_b128 v[156:159], v156 offset:3072
	ds_read_b128 v[160:163], v172
	ds_read_b128 v[164:167], v172 offset:1024
	ds_read_b128 v[168:171], v172 offset:2048
	ds_read_b128 v[172:175], v172 offset:3072
	s_add_u32 s24, s24, 0x40000
	s_addc_u32 s25, s25, 0
	s_mov_b32 m0, s31
	ds_read_b128 v[176:179], v143 offset:32768
	ds_read_b128 v[180:183], v143 offset:33792
	ds_read_b128 v[184:187], v143 offset:34816
	ds_read_b128 v[188:191], v143 offset:35840
	ds_read_b128 v[192:195], v143 offset:36864
	ds_read_b128 v[196:199], v143 offset:37888
	ds_read_b128 v[200:203], v143 offset:38912
	ds_read_b128 v[204:207], v143 offset:39936
	global_load_lds_dwordx4 v132, s[24:25]
	s_mov_b32 m0, s34
	s_nop 0
	global_load_lds_dwordx4 v130, s[24:25]
	s_waitcnt vmcnt(8)
	s_waitcnt lgkmcnt(0)
	s_barrier
	s_setprio 1
	s_waitcnt lgkmcnt(0)
	v_mfma_f32_16x16x32_bf16 v[124:127], v[144:147], v[176:179], v[124:127]
	v_mfma_f32_16x16x32_bf16 v[120:123], v[152:155], v[176:179], v[120:123]
	v_mfma_f32_16x16x32_bf16 v[108:111], v[144:147], v[184:187], v[108:111]
	v_mfma_f32_16x16x32_bf16 v[104:107], v[152:155], v[184:187], v[104:107]
	v_mfma_f32_16x16x32_bf16 v[92:95], v[144:147], v[192:195], v[92:95]
	v_mfma_f32_16x16x32_bf16 v[88:91], v[152:155], v[192:195], v[88:91]
	v_mfma_f32_16x16x32_bf16 v[76:79], v[144:147], v[200:203], v[76:79]
	v_mfma_f32_16x16x32_bf16 v[72:75], v[152:155], v[200:203], v[72:75]
	v_mfma_f32_16x16x32_bf16 v[124:127], v[148:151], v[180:183], v[124:127]
	v_mfma_f32_16x16x32_bf16 v[120:123], v[156:159], v[180:183], v[120:123]
	v_mfma_f32_16x16x32_bf16 v[108:111], v[148:151], v[188:191], v[108:111]
	v_mfma_f32_16x16x32_bf16 v[104:107], v[156:159], v[188:191], v[104:107]
	v_mfma_f32_16x16x32_bf16 v[92:95], v[148:151], v[196:199], v[92:95]
	v_mfma_f32_16x16x32_bf16 v[88:91], v[156:159], v[196:199], v[88:91]
	v_mfma_f32_16x16x32_bf16 v[76:79], v[148:151], v[204:207], v[76:79]
	v_mfma_f32_16x16x32_bf16 v[72:75], v[156:159], v[204:207], v[72:75]
	s_setprio 0
	s_setprio 1
	v_mfma_f32_16x16x32_bf16 v[116:119], v[160:163], v[176:179], v[116:119]
	v_mfma_f32_16x16x32_bf16 v[112:115], v[168:171], v[176:179], v[112:115]
	v_mfma_f32_16x16x32_bf16 v[100:103], v[160:163], v[184:187], v[100:103]
	v_mfma_f32_16x16x32_bf16 v[96:99], v[168:171], v[184:187], v[96:99]
	v_mfma_f32_16x16x32_bf16 v[84:87], v[160:163], v[192:195], v[84:87]
	v_mfma_f32_16x16x32_bf16 v[80:83], v[168:171], v[192:195], v[80:83]
	v_mfma_f32_16x16x32_bf16 v[68:71], v[160:163], v[200:203], v[68:71]
	v_mfma_f32_16x16x32_bf16 v[64:67], v[168:171], v[200:203], v[64:67]
	v_mfma_f32_16x16x32_bf16 v[116:119], v[164:167], v[180:183], v[116:119]
	v_mfma_f32_16x16x32_bf16 v[112:115], v[172:175], v[180:183], v[112:115]
	v_mfma_f32_16x16x32_bf16 v[100:103], v[164:167], v[188:191], v[100:103]
	v_mfma_f32_16x16x32_bf16 v[96:99], v[172:175], v[188:191], v[96:99]
	v_mfma_f32_16x16x32_bf16 v[84:87], v[164:167], v[196:199], v[84:87]
	v_mfma_f32_16x16x32_bf16 v[80:83], v[172:175], v[196:199], v[80:83]
	v_mfma_f32_16x16x32_bf16 v[68:71], v[164:167], v[204:207], v[68:71]
	v_mfma_f32_16x16x32_bf16 v[64:67], v[172:175], v[204:207], v[64:67]
	s_setprio 0
	s_barrier
	s_add_i32 s10, s10, s28
	v_lshl_add_u64 v[138:139], v[138:139], 0, s[94:95]
	s_mov_b32 m0, s10
	ds_read_b128 v[176:179], v143 offset:49152
	ds_read_b128 v[180:183], v143 offset:50176
	ds_read_b128 v[184:187], v143 offset:51200
	ds_read_b128 v[188:191], v143 offset:52224
	ds_read_b128 v[192:195], v143 offset:53248
	ds_read_b128 v[196:199], v143 offset:54272
	ds_read_b128 v[200:203], v143 offset:55296
	ds_read_b128 v[204:207], v143 offset:56320
	global_load_lds_dwordx4 v[138:139], off
	s_add_i32 m0, s10, 0x2000
	s_add_u32 s22, s22, 0x40080
	v_lshl_add_u64 v[138:139], v[222:223], 0, s[94:95]
	s_addc_u32 s23, s23, 0
	s_add_i32 s10, s11, s28
	global_load_lds_dwordx4 v[138:139], off
	s_mov_b32 m0, s10
	s_nop 0
	global_load_lds_dwordx4 v208, s[22:23]
	v_lshl_add_u64 v[138:139], s[22:23], 0, v[128:129]
	s_add_i32 m0, s10, 0x2000
	s_nop 0
	global_load_lds_dwordx4 v[138:139], off
	v_lshl_add_u64 v[138:139], v[224:225], 0, s[94:95]
	s_mov_b32 m0, s35
	s_nop 0
	global_load_lds_dwordx4 v[138:139], off
	v_lshl_add_u64 v[138:139], v[236:237], 0, s[94:95]
	s_mov_b32 m0, s36
	s_nop 0
	global_load_lds_dwordx4 v[138:139], off
	s_waitcnt vmcnt(8)
	s_waitcnt lgkmcnt(0)
	s_barrier
	s_setprio 1
	s_waitcnt lgkmcnt(0)
	v_mfma_f32_16x16x32_bf16 v[60:63], v[144:147], v[176:179], v[60:63]
	v_mfma_f32_16x16x32_bf16 v[56:59], v[152:155], v[176:179], v[56:59]
	v_mfma_f32_16x16x32_bf16 v[44:47], v[144:147], v[184:187], v[44:47]
	v_mfma_f32_16x16x32_bf16 v[40:43], v[152:155], v[184:187], v[40:43]
	v_mfma_f32_16x16x32_bf16 v[28:31], v[144:147], v[192:195], v[28:31]
	v_mfma_f32_16x16x32_bf16 v[24:27], v[152:155], v[192:195], v[24:27]
	v_mfma_f32_16x16x32_bf16 v[12:15], v[144:147], v[200:203], v[12:15]
	v_mfma_f32_16x16x32_bf16 v[8:11], v[152:155], v[200:203], v[8:11]
	v_mfma_f32_16x16x32_bf16 v[60:63], v[148:151], v[180:183], v[60:63]
	v_mfma_f32_16x16x32_bf16 v[56:59], v[156:159], v[180:183], v[56:59]
	v_mfma_f32_16x16x32_bf16 v[44:47], v[148:151], v[188:191], v[44:47]
	v_mfma_f32_16x16x32_bf16 v[40:43], v[156:159], v[188:191], v[40:43]
	v_mfma_f32_16x16x32_bf16 v[28:31], v[148:151], v[196:199], v[28:31]
	v_mfma_f32_16x16x32_bf16 v[24:27], v[156:159], v[196:199], v[24:27]
	v_mfma_f32_16x16x32_bf16 v[12:15], v[148:151], v[204:207], v[12:15]
	v_mfma_f32_16x16x32_bf16 v[8:11], v[156:159], v[204:207], v[8:11]
	s_setprio 0
	s_setprio 1
	v_mfma_f32_16x16x32_bf16 v[52:55], v[160:163], v[176:179], v[52:55]
	v_mfma_f32_16x16x32_bf16 v[48:51], v[168:171], v[176:179], v[48:51]
	v_mfma_f32_16x16x32_bf16 v[36:39], v[160:163], v[184:187], v[36:39]
	v_mfma_f32_16x16x32_bf16 v[32:35], v[168:171], v[184:187], v[32:35]
	v_mfma_f32_16x16x32_bf16 v[20:23], v[160:163], v[192:195], v[20:23]
	v_mfma_f32_16x16x32_bf16 v[16:19], v[168:171], v[192:195], v[16:19]
	v_mfma_f32_16x16x32_bf16 v[4:7], v[160:163], v[200:203], v[4:7]
	v_mfma_f32_16x16x32_bf16 v[0:3], v[168:171], v[200:203], v[0:3]
	v_mfma_f32_16x16x32_bf16 v[52:55], v[164:167], v[180:183], v[52:55]
	v_mfma_f32_16x16x32_bf16 v[48:51], v[172:175], v[180:183], v[48:51]
	v_mfma_f32_16x16x32_bf16 v[36:39], v[164:167], v[188:191], v[36:39]
	v_mfma_f32_16x16x32_bf16 v[32:35], v[172:175], v[188:191], v[32:35]
	v_mfma_f32_16x16x32_bf16 v[20:23], v[164:167], v[196:199], v[20:23]
	v_mfma_f32_16x16x32_bf16 v[16:19], v[172:175], v[196:199], v[16:19]
	v_mfma_f32_16x16x32_bf16 v[4:7], v[164:167], v[204:207], v[4:7]
	v_mfma_f32_16x16x32_bf16 v[0:3], v[172:175], v[204:207], v[0:3]
	s_setprio 0
	s_barrier
	s_add_i32 s82, s82, 2
	s_add_u32 s20, s20, 0x100
	s_addc_u32 s21, s21, 0
	s_add_u32 s70, s70, 0x100
	s_addc_u32 s80, s80, 0
	s_cmp_gt_u32 s82, 13
	s_cbranch_scc0 .LBB0_795
	v_lshl_add_u32 v138, s40, 8, v140
	v_ashrrev_i32_e32 v139, 31, v138
	v_lshl_add_u64 v[146:147], v[138:139], 2, s[76:77]
	global_load_dword v160, v[146:147], off
	global_load_dword v161, v[146:147], off offset:64
	global_load_dword v162, v[146:147], off offset:128
	global_load_dword v163, v[146:147], off offset:192
	global_load_dword v164, v[146:147], off offset:512
	global_load_dword v165, v[146:147], off offset:576
	global_load_dword v166, v[146:147], off offset:640
	global_load_dword v167, v[146:147], off offset:704
	s_and_b64 vcc, exec, s[6:7]
	s_cbranch_vccz .LBB0_798
	s_barrier

.LBB0_869:
	s_add_u32 s10, s24, 0xfff00080
	s_addc_u32 s11, s25, -1
	s_add_i32 s83, 0, 0x10000
	s_cmp_eq_u32 s82, 60
	s_cselect_b32 s29, s19, s11
	s_cselect_b32 s28, s72, s10
	v_add_u32_e32 v142, s83, v145
	s_cselect_b32 s27, s17, s80
	s_cselect_b32 s26, s76, s77
	s_add_i32 s10, 0, 0x14000
	ds_read_b128 v[138:141], v142
	ds_read_b128 v[148:151], v142 offset:1024
	ds_read_b128 v[152:155], v142 offset:2048
	ds_read_b128 v[156:159], v142 offset:3072
	v_add_u32_e32 v142, s10, v145
	ds_read_b128 v[160:163], v142
	ds_read_b128 v[164:167], v142 offset:1024
	ds_read_b128 v[168:171], v142 offset:2048
	ds_read_b128 v[172:175], v142 offset:3072
	s_add_i32 m0, s34, 0xc000
	ds_read_b128 v[176:179], v147
	ds_read_b128 v[180:183], v147 offset:1024
	ds_read_b128 v[184:187], v147 offset:2048
	ds_read_b128 v[188:191], v147 offset:3072
	ds_read_b128 v[192:195], v147 offset:4096
	ds_read_b128 v[196:199], v147 offset:5120
	ds_read_b128 v[200:203], v147 offset:6144
	ds_read_b128 v[204:207], v147 offset:7168
	global_load_lds_dwordx4 v134, s[24:25]
	s_add_i32 m0, s34, 0xe000
	s_nop 0
	global_load_lds_dwordx4 v136, s[24:25]
	s_waitcnt vmcnt(8)
	s_waitcnt lgkmcnt(0)
	s_barrier
	s_setprio 1
	s_waitcnt lgkmcnt(0)
	v_mfma_f32_16x16x32_bf16 v[124:127], v[138:141], v[176:179], v[124:127]
	v_mfma_f32_16x16x32_bf16 v[120:123], v[152:155], v[176:179], v[120:123]
	v_mfma_f32_16x16x32_bf16 v[108:111], v[138:141], v[184:187], v[108:111]
	v_mfma_f32_16x16x32_bf16 v[104:107], v[152:155], v[184:187], v[104:107]
	v_mfma_f32_16x16x32_bf16 v[92:95], v[138:141], v[192:195], v[92:95]
	v_mfma_f32_16x16x32_bf16 v[88:91], v[152:155], v[192:195], v[88:91]
	v_mfma_f32_16x16x32_bf16 v[76:79], v[138:141], v[200:203], v[76:79]
	v_mfma_f32_16x16x32_bf16 v[72:75], v[152:155], v[200:203], v[72:75]
	v_mfma_f32_16x16x32_bf16 v[124:127], v[148:151], v[180:183], v[124:127]
	v_mfma_f32_16x16x32_bf16 v[120:123], v[156:159], v[180:183], v[120:123]
	v_mfma_f32_16x16x32_bf16 v[108:111], v[148:151], v[188:191], v[108:111]
	v_mfma_f32_16x16x32_bf16 v[104:107], v[156:159], v[188:191], v[104:107]
	v_mfma_f32_16x16x32_bf16 v[92:95], v[148:151], v[196:199], v[92:95]
	v_mfma_f32_16x16x32_bf16 v[88:91], v[156:159], v[196:199], v[88:91]
	v_mfma_f32_16x16x32_bf16 v[76:79], v[148:151], v[204:207], v[76:79]
	v_mfma_f32_16x16x32_bf16 v[72:75], v[156:159], v[204:207], v[72:75]
	s_setprio 0
	s_setprio 1
	v_mfma_f32_16x16x32_bf16 v[116:119], v[160:163], v[176:179], v[116:119]
	v_mfma_f32_16x16x32_bf16 v[112:115], v[168:171], v[176:179], v[112:115]
	v_mfma_f32_16x16x32_bf16 v[100:103], v[160:163], v[184:187], v[100:103]
	v_mfma_f32_16x16x32_bf16 v[96:99], v[168:171], v[184:187], v[96:99]
	v_mfma_f32_16x16x32_bf16 v[84:87], v[160:163], v[192:195], v[84:87]
	v_mfma_f32_16x16x32_bf16 v[80:83], v[168:171], v[192:195], v[80:83]
	v_mfma_f32_16x16x32_bf16 v[68:71], v[160:163], v[200:203], v[68:71]
	v_mfma_f32_16x16x32_bf16 v[64:67], v[168:171], v[200:203], v[64:67]
	v_mfma_f32_16x16x32_bf16 v[116:119], v[164:167], v[180:183], v[116:119]
	v_mfma_f32_16x16x32_bf16 v[112:115], v[172:175], v[180:183], v[112:115]
	v_mfma_f32_16x16x32_bf16 v[100:103], v[164:167], v[188:191], v[100:103]
	v_mfma_f32_16x16x32_bf16 v[96:99], v[172:175], v[188:191], v[96:99]
	v_mfma_f32_16x16x32_bf16 v[84:87], v[164:167], v[196:199], v[84:87]
	v_mfma_f32_16x16x32_bf16 v[80:83], v[172:175], v[196:199], v[80:83]
	v_mfma_f32_16x16x32_bf16 v[68:71], v[164:167], v[204:207], v[68:71]
	v_mfma_f32_16x16x32_bf16 v[64:67], v[172:175], v[204:207], v[64:67]
	s_setprio 0
	s_barrier
	s_add_i32 s11, s83, s31
	v_lshl_add_u64 v[142:143], s[26:27], 0, v[208:209]
	s_mov_b32 m0, s11
	ds_read_b128 v[176:179], v147 offset:16384
	ds_read_b128 v[180:183], v147 offset:17408
	ds_read_b128 v[184:187], v147 offset:18432
	ds_read_b128 v[188:191], v147 offset:19456
	ds_read_b128 v[192:195], v147 offset:20480
	ds_read_b128 v[196:199], v147 offset:21504
	ds_read_b128 v[200:203], v147 offset:22528
	ds_read_b128 v[204:207], v147 offset:23552
	global_load_lds_dwordx4 v[142:143], off
	s_add_i32 m0, s11, 0x2000
	s_add_u32 s96, s26, 0x100000
	v_lshl_add_u64 v[222:223], s[26:27], 0, v[128:129]
	s_addc_u32 s97, s27, 0
	s_add_i32 s10, s10, s31
	global_load_lds_dwordx4 v[222:223], off
	s_mov_b32 m0, s10
	v_lshl_add_u64 v[236:237], s[28:29], 0, v[130:131]
	global_load_lds_dwordx4 v208, s[96:97]
	s_add_i32 m0, s10, 0x2000
	s_nop 0
	global_load_lds_dwordx4 v128, s[96:97]
	v_lshl_add_u64 v[224:225], s[28:29], 0, v[132:133]
	s_mov_b32 m0, s34
	s_nop 0
	global_load_lds_dwordx4 v[224:225], off
	s_mov_b32 m0, s35
	s_nop 0
	global_load_lds_dwordx4 v[236:237], off
	s_waitcnt vmcnt(8)
	s_waitcnt lgkmcnt(0)
	s_barrier
	s_setprio 1
	s_waitcnt lgkmcnt(0)
	v_mfma_f32_16x16x32_bf16 v[60:63], v[138:141], v[176:179], v[60:63]
	v_mfma_f32_16x16x32_bf16 v[56:59], v[152:155], v[176:179], v[56:59]
	v_mfma_f32_16x16x32_bf16 v[44:47], v[138:141], v[184:187], v[44:47]
	v_mfma_f32_16x16x32_bf16 v[40:43], v[152:155], v[184:187], v[40:43]
	v_mfma_f32_16x16x32_bf16 v[28:31], v[138:141], v[192:195], v[28:31]
	v_mfma_f32_16x16x32_bf16 v[24:27], v[152:155], v[192:195], v[24:27]
	v_mfma_f32_16x16x32_bf16 v[12:15], v[138:141], v[200:203], v[12:15]
	v_mfma_f32_16x16x32_bf16 v[8:11], v[152:155], v[200:203], v[8:11]
	v_mfma_f32_16x16x32_bf16 v[60:63], v[148:151], v[180:183], v[60:63]
	v_mfma_f32_16x16x32_bf16 v[56:59], v[156:159], v[180:183], v[56:59]
	v_mfma_f32_16x16x32_bf16 v[44:47], v[148:151], v[188:191], v[44:47]
	v_mfma_f32_16x16x32_bf16 v[40:43], v[156:159], v[188:191], v[40:43]
	v_mfma_f32_16x16x32_bf16 v[28:31], v[148:151], v[196:199], v[28:31]
	v_mfma_f32_16x16x32_bf16 v[24:27], v[156:159], v[196:199], v[24:27]
	v_mfma_f32_16x16x32_bf16 v[12:15], v[148:151], v[204:207], v[12:15]
	v_mfma_f32_16x16x32_bf16 v[8:11], v[156:159], v[204:207], v[8:11]
	s_setprio 0
	s_setprio 1
	v_mfma_f32_16x16x32_bf16 v[52:55], v[160:163], v[176:179], v[52:55]
	v_mfma_f32_16x16x32_bf16 v[48:51], v[168:171], v[176:179], v[48:51]
	v_mfma_f32_16x16x32_bf16 v[36:39], v[160:163], v[184:187], v[36:39]
	v_mfma_f32_16x16x32_bf16 v[32:35], v[168:171], v[184:187], v[32:35]
	v_mfma_f32_16x16x32_bf16 v[20:23], v[160:163], v[192:195], v[20:23]
	v_mfma_f32_16x16x32_bf16 v[16:19], v[168:171], v[192:195], v[16:19]
	v_mfma_f32_16x16x32_bf16 v[4:7], v[160:163], v[200:203], v[4:7]
	v_mfma_f32_16x16x32_bf16 v[0:3], v[168:171], v[200:203], v[0:3]
	v_mfma_f32_16x16x32_bf16 v[52:55], v[164:167], v[180:183], v[52:55]
	v_mfma_f32_16x16x32_bf16 v[48:51], v[172:175], v[180:183], v[48:51]
	v_mfma_f32_16x16x32_bf16 v[36:39], v[164:167], v[188:191], v[36:39]
	v_mfma_f32_16x16x32_bf16 v[32:35], v[172:175], v[188:191], v[32:35]
	v_mfma_f32_16x16x32_bf16 v[20:23], v[164:167], v[196:199], v[20:23]
	v_mfma_f32_16x16x32_bf16 v[16:19], v[172:175], v[196:199], v[16:19]
	v_mfma_f32_16x16x32_bf16 v[4:7], v[164:167], v[204:207], v[4:7]
	v_mfma_f32_16x16x32_bf16 v[0:3], v[172:175], v[204:207], v[0:3]
	s_setprio 0
	s_barrier
	s_add_i32 s10, 0, 0x18000
	s_add_i32 s11, 0, 0x1c000
	v_add_u32_e32 v156, s10, v145
	v_add_u32_e32 v172, s11, v145
	ds_read_b128 v[138:141], v156
	ds_read_b128 v[148:151], v156 offset:1024
	ds_read_b128 v[152:155], v156 offset:2048
	ds_read_b128 v[156:159], v156 offset:3072
	ds_read_b128 v[160:163], v172
	ds_read_b128 v[164:167], v172 offset:1024
	ds_read_b128 v[168:171], v172 offset:2048
	ds_read_b128 v[172:175], v172 offset:3072
	s_add_u32 s28, s28, 0x100000
	s_addc_u32 s29, s29, 0
	s_mov_b32 m0, s36
	ds_read_b128 v[176:179], v147 offset:32768
	ds_read_b128 v[180:183], v147 offset:33792
	ds_read_b128 v[184:187], v147 offset:34816
	ds_read_b128 v[188:191], v147 offset:35840
	ds_read_b128 v[192:195], v147 offset:36864
	ds_read_b128 v[196:199], v147 offset:37888
	ds_read_b128 v[200:203], v147 offset:38912
	ds_read_b128 v[204:207], v147 offset:39936
	global_load_lds_dwordx4 v132, s[28:29]
	s_mov_b32 m0, s37
	s_nop 0
	global_load_lds_dwordx4 v130, s[28:29]
	s_waitcnt vmcnt(8)
	s_waitcnt lgkmcnt(0)
	s_barrier
	s_setprio 1
	s_waitcnt lgkmcnt(0)
	v_mfma_f32_16x16x32_bf16 v[124:127], v[138:141], v[176:179], v[124:127]
	v_mfma_f32_16x16x32_bf16 v[120:123], v[152:155], v[176:179], v[120:123]
	v_mfma_f32_16x16x32_bf16 v[108:111], v[138:141], v[184:187], v[108:111]
	v_mfma_f32_16x16x32_bf16 v[104:107], v[152:155], v[184:187], v[104:107]
	v_mfma_f32_16x16x32_bf16 v[92:95], v[138:141], v[192:195], v[92:95]
	v_mfma_f32_16x16x32_bf16 v[88:91], v[152:155], v[192:195], v[88:91]
	v_mfma_f32_16x16x32_bf16 v[76:79], v[138:141], v[200:203], v[76:79]
	v_mfma_f32_16x16x32_bf16 v[72:75], v[152:155], v[200:203], v[72:75]
	v_mfma_f32_16x16x32_bf16 v[124:127], v[148:151], v[180:183], v[124:127]
	v_mfma_f32_16x16x32_bf16 v[120:123], v[156:159], v[180:183], v[120:123]
	v_mfma_f32_16x16x32_bf16 v[108:111], v[148:151], v[188:191], v[108:111]
	v_mfma_f32_16x16x32_bf16 v[104:107], v[156:159], v[188:191], v[104:107]
	v_mfma_f32_16x16x32_bf16 v[92:95], v[148:151], v[196:199], v[92:95]
	v_mfma_f32_16x16x32_bf16 v[88:91], v[156:159], v[196:199], v[88:91]
	v_mfma_f32_16x16x32_bf16 v[76:79], v[148:151], v[204:207], v[76:79]
	v_mfma_f32_16x16x32_bf16 v[72:75], v[156:159], v[204:207], v[72:75]
	s_setprio 0
	s_setprio 1
	v_mfma_f32_16x16x32_bf16 v[116:119], v[160:163], v[176:179], v[116:119]
	v_mfma_f32_16x16x32_bf16 v[112:115], v[168:171], v[176:179], v[112:115]
	v_mfma_f32_16x16x32_bf16 v[100:103], v[160:163], v[184:187], v[100:103]
	v_mfma_f32_16x16x32_bf16 v[96:99], v[168:171], v[184:187], v[96:99]
	v_mfma_f32_16x16x32_bf16 v[84:87], v[160:163], v[192:195], v[84:87]
	v_mfma_f32_16x16x32_bf16 v[80:83], v[168:171], v[192:195], v[80:83]
	v_mfma_f32_16x16x32_bf16 v[68:71], v[160:163], v[200:203], v[68:71]
	v_mfma_f32_16x16x32_bf16 v[64:67], v[168:171], v[200:203], v[64:67]
	v_mfma_f32_16x16x32_bf16 v[116:119], v[164:167], v[180:183], v[116:119]
	v_mfma_f32_16x16x32_bf16 v[112:115], v[172:175], v[180:183], v[112:115]
	v_mfma_f32_16x16x32_bf16 v[100:103], v[164:167], v[188:191], v[100:103]
	v_mfma_f32_16x16x32_bf16 v[96:99], v[172:175], v[188:191], v[96:99]
	v_mfma_f32_16x16x32_bf16 v[84:87], v[164:167], v[196:199], v[84:87]
	v_mfma_f32_16x16x32_bf16 v[80:83], v[172:175], v[196:199], v[80:83]
	v_mfma_f32_16x16x32_bf16 v[68:71], v[164:167], v[204:207], v[68:71]
	v_mfma_f32_16x16x32_bf16 v[64:67], v[172:175], v[204:207], v[64:67]
	s_setprio 0
	s_barrier
	s_add_i32 s10, s10, s31
	v_lshl_add_u64 v[142:143], v[142:143], 0, s[94:95]
	s_mov_b32 m0, s10
	ds_read_b128 v[176:179], v147 offset:49152
	ds_read_b128 v[180:183], v147 offset:50176
	ds_read_b128 v[184:187], v147 offset:51200
	ds_read_b128 v[188:191], v147 offset:52224
	ds_read_b128 v[192:195], v147 offset:53248
	ds_read_b128 v[196:199], v147 offset:54272
	ds_read_b128 v[200:203], v147 offset:55296
	ds_read_b128 v[204:207], v147 offset:56320
	global_load_lds_dwordx4 v[142:143], off
	s_add_i32 m0, s10, 0x2000
	s_add_u32 s26, s26, 0x100080
	v_lshl_add_u64 v[142:143], v[222:223], 0, s[94:95]
	s_addc_u32 s27, s27, 0
	s_add_i32 s10, s11, s31
	global_load_lds_dwordx4 v[142:143], off
	s_mov_b32 m0, s10
	s_nop 0
	global_load_lds_dwordx4 v208, s[26:27]
	v_lshl_add_u64 v[142:143], s[26:27], 0, v[128:129]
	s_add_i32 m0, s10, 0x2000
	s_nop 0
	global_load_lds_dwordx4 v[142:143], off
	v_lshl_add_u64 v[142:143], v[224:225], 0, s[94:95]
	s_mov_b32 m0, s40
	s_nop 0
	global_load_lds_dwordx4 v[142:143], off
	v_lshl_add_u64 v[142:143], v[236:237], 0, s[94:95]
	s_mov_b32 m0, s41
	s_nop 0
	global_load_lds_dwordx4 v[142:143], off
	s_waitcnt vmcnt(8)
	s_waitcnt lgkmcnt(0)
	s_barrier
	s_setprio 1
	s_waitcnt lgkmcnt(0)
	v_mfma_f32_16x16x32_bf16 v[60:63], v[138:141], v[176:179], v[60:63]
	v_mfma_f32_16x16x32_bf16 v[56:59], v[152:155], v[176:179], v[56:59]
	v_mfma_f32_16x16x32_bf16 v[44:47], v[138:141], v[184:187], v[44:47]
	v_mfma_f32_16x16x32_bf16 v[40:43], v[152:155], v[184:187], v[40:43]
	v_mfma_f32_16x16x32_bf16 v[28:31], v[138:141], v[192:195], v[28:31]
	v_mfma_f32_16x16x32_bf16 v[24:27], v[152:155], v[192:195], v[24:27]
	v_mfma_f32_16x16x32_bf16 v[12:15], v[138:141], v[200:203], v[12:15]
	v_mfma_f32_16x16x32_bf16 v[8:11], v[152:155], v[200:203], v[8:11]
	v_mfma_f32_16x16x32_bf16 v[60:63], v[148:151], v[180:183], v[60:63]
	v_mfma_f32_16x16x32_bf16 v[56:59], v[156:159], v[180:183], v[56:59]
	v_mfma_f32_16x16x32_bf16 v[44:47], v[148:151], v[188:191], v[44:47]
	v_mfma_f32_16x16x32_bf16 v[40:43], v[156:159], v[188:191], v[40:43]
	v_mfma_f32_16x16x32_bf16 v[28:31], v[148:151], v[196:199], v[28:31]
	v_mfma_f32_16x16x32_bf16 v[24:27], v[156:159], v[196:199], v[24:27]
	v_mfma_f32_16x16x32_bf16 v[12:15], v[148:151], v[204:207], v[12:15]
	v_mfma_f32_16x16x32_bf16 v[8:11], v[156:159], v[204:207], v[8:11]
	s_setprio 0
	s_setprio 1
	v_mfma_f32_16x16x32_bf16 v[52:55], v[160:163], v[176:179], v[52:55]
	v_mfma_f32_16x16x32_bf16 v[48:51], v[168:171], v[176:179], v[48:51]
	v_mfma_f32_16x16x32_bf16 v[36:39], v[160:163], v[184:187], v[36:39]
	v_mfma_f32_16x16x32_bf16 v[32:35], v[168:171], v[184:187], v[32:35]
	v_mfma_f32_16x16x32_bf16 v[20:23], v[160:163], v[192:195], v[20:23]
	v_mfma_f32_16x16x32_bf16 v[16:19], v[168:171], v[192:195], v[16:19]
	v_mfma_f32_16x16x32_bf16 v[4:7], v[160:163], v[200:203], v[4:7]
	v_mfma_f32_16x16x32_bf16 v[0:3], v[168:171], v[200:203], v[0:3]
	v_mfma_f32_16x16x32_bf16 v[52:55], v[164:167], v[180:183], v[52:55]
	v_mfma_f32_16x16x32_bf16 v[48:51], v[172:175], v[180:183], v[48:51]
	v_mfma_f32_16x16x32_bf16 v[36:39], v[164:167], v[188:191], v[36:39]
	v_mfma_f32_16x16x32_bf16 v[32:35], v[172:175], v[188:191], v[32:35]
	v_mfma_f32_16x16x32_bf16 v[20:23], v[164:167], v[196:199], v[20:23]
	v_mfma_f32_16x16x32_bf16 v[16:19], v[172:175], v[196:199], v[16:19]
	v_mfma_f32_16x16x32_bf16 v[4:7], v[164:167], v[204:207], v[4:7]
	v_mfma_f32_16x16x32_bf16 v[0:3], v[172:175], v[204:207], v[0:3]
	s_setprio 0
	s_barrier
	s_add_i32 s82, s82, 2
	s_add_u32 s24, s24, 0x100
	s_addc_u32 s25, s25, 0
	s_add_u32 s77, s77, 0x100
	s_addc_u32 s80, s80, 0
	s_cmp_gt_u32 s82, 61
	s_cbranch_scc0 .LBB0_869
	v_lshl_add_u32 v140, s70, 8, v144
	v_lshl_or_b32 v138, s43, 8, v146
	v_lshlrev_b32_e32 v139, 2, v140
	v_lshlrev_b32_e32 v140, 11, v140
	v_lshl_add_u32 v138, v138, 1, v140
	s_mov_b64 s[100:101], s[46:47]
	global_load_dwordx4 v[148:151], v138, s[100:101]
	global_load_dwordx4 v[152:155], v138, s[100:101] offset:256
	s_add_u32 s100, s100, 0x8000
	s_addc_u32 s101, s101, 0
	global_load_dwordx4 v[156:159], v138, s[100:101]
	global_load_dwordx4 v[160:163], v138, s[100:101] offset:256
	s_add_u32 s100, s100, 0x8000
	s_addc_u32 s101, s101, 0
	global_load_dwordx4 v[164:167], v138, s[100:101]
	global_load_dwordx4 v[168:171], v138, s[100:101] offset:256
	s_add_u32 s100, s100, 0x8000
	s_addc_u32 s101, s101, 0
	global_load_dwordx4 v[172:175], v138, s[100:101]
	global_load_dwordx4 v[176:179], v138, s[100:101] offset:256
	s_add_u32 s100, s100, 0x28000
	s_addc_u32 s101, s101, 0
	global_load_dwordx4 v[180:183], v138, s[100:101]
	global_load_dwordx4 v[184:187], v138, s[100:101] offset:256
	s_add_u32 s100, s100, 0x8000
	s_addc_u32 s101, s101, 0
	global_load_dwordx4 v[188:191], v138, s[100:101]
	global_load_dwordx4 v[192:195], v138, s[100:101] offset:256
	s_add_u32 s100, s100, 0x8000
	s_addc_u32 s101, s101, 0
	global_load_dwordx4 v[196:199], v138, s[100:101]
	global_load_dwordx4 v[200:203], v138, s[100:101] offset:256
	s_add_u32 s100, s100, 0x8000
	s_addc_u32 s101, s101, 0
	global_load_dwordx4 v[204:207], v138, s[100:101]
	global_load_dwordx4 v[236:239], v138, s[100:101] offset:256
	s_and_b64 vcc, exec, s[14:15]
	s_cbranch_vccz .LBB0_872
	s_barrier
